# sb_item output gate loads prefetched; grid-barrier census loads issued together
# baseline (speedup 1.0000x reference)
; DI unsigned pk2(float a, float b) { f32x2 v = {a, b}; return __builtin_bit_cast(unsigned, __builtin_convertvector(v, bf2_t)); }
; DI float bf_lo(unsigned u) { return __uint_as_float(u << 16); }
; DI float bf_hi(unsigned u) { return __uint_as_float(u & 0xffff0000u); }
; DI void sb_item(const Params& P, int b, int hd, int qt, char* lds) {
;     ...
; #pragma unroll
;     for (int db = 0; db < 2; ++db)
; #pragma unroll
;         for (int q4 = 0; q4 < 4; ++q4) {
;             const int dv = 32 * db + 8 * q4 + 4 * h;
;             const u32x2 z2 = *(const u32x2*)(sz + tokq * 512 + hd * 64 + dv);
;             u32x2 o = {pk2(O[db][4 * q4] * bf_lo(z2[0]), O[db][4 * q4 + 1] * bf_hi(z2[0])), pk2(O[db][4 * q4 + 2] * bf_lo(z2[1]), O[db][4 * q4 + 3] * bf_hi(z2[1]))};
;             *(u32x2*)(sq + tokq * 512 + hd * 64 + dv) = o;
;         }
;     __syncthreads();
; DI void attn_phase(const Params& P, int layer, char* lds) {
;     ...
;     for (int i = blockIdx.x; i < 1024; i += gridDim.x) {
;         const int x = i & 7, j = i >> 3, bh = x * 4 + (j >> 5), qt = j & 31;
;         sb_item(P, bh >> 3, bh & 7, qt, lds);
.LBB0_145:
	s_or_b64 exec, exec, s[20:21]
	v_readlane_b32 s6, v253, 61
	v_readlane_b32 s7, v253, 62
	s_lshl_b32 s82, s3, 1
	v_lshlrev_b32_e32 v0, 1, v95
	v_lshl_add_u64 v[34:35], s[6:7], 0, v[86:87]
	v_lshl_add_u64 v[34:35], v[34:35], 0, s[82:83]
	v_lshl_add_u64 v[34:35], v[34:35], 0, v[0:1]
	global_load_dwordx2 v[204:205], v[34:35], off
	global_load_dwordx2 v[206:207], v[34:35], off offset:16
	global_load_dwordx2 v[208:209], v[34:35], off offset:32
	global_load_dwordx2 v[210:211], v[34:35], off offset:48
	global_load_dwordx2 v[212:213], v[34:35], off offset:64
	global_load_dwordx2 v[214:215], v[34:35], off offset:80
	global_load_dwordx2 v[216:217], v[34:35], off offset:96
	global_load_dwordx2 v[218:219], v[34:35], off offset:112
	v_lshl_add_u64 v[36:37], v[84:85], 0, s[82:83]
	v_readlane_b32 s6, v253, 30
	v_readlane_b32 s7, v253, 31
	s_waitcnt vmcnt(7)
	s_nop 1
	v_mov_b64_e32 v[38:39], v[204:205]
	v_lshlrev_b32_e32 v40, 16, v38
	v_and_b32_e32 v41, 0xffff0000, v38
	v_pk_mul_f32 v[18:19], v[18:19], v[40:41]
	s_nop 0
	v_cvt_pk_bf16_f32 v38, v18, v19
	v_lshlrev_b32_e32 v18, 16, v39
	v_and_b32_e32 v19, 0xffff0000, v39
	v_pk_mul_f32 v[18:19], v[20:21], v[18:19]
	v_cvt_pk_bf16_f32 v39, v18, v19
	v_lshl_add_u64 v[18:19], v[36:37], 0, v[0:1]
	global_store_dwordx2 v[18:19], v[38:39], off
	s_waitcnt vmcnt(7)
	s_nop 1
	v_mov_b64_e32 v[20:21], v[206:207]
	v_lshlrev_b32_e32 v36, 16, v20
	v_and_b32_e32 v37, 0xffff0000, v20
	v_pk_mul_f32 v[22:23], v[22:23], v[36:37]
	s_nop 0
	v_cvt_pk_bf16_f32 v20, v22, v23
	v_lshlrev_b32_e32 v22, 16, v21
	v_and_b32_e32 v23, 0xffff0000, v21
	v_pk_mul_f32 v[22:23], v[24:25], v[22:23]
	s_nop 0
	v_cvt_pk_bf16_f32 v21, v22, v23
	global_store_dwordx2 v[18:19], v[20:21], off offset:16
	s_waitcnt vmcnt(7)
	s_nop 1
	v_mov_b64_e32 v[20:21], v[208:209]
	v_lshlrev_b32_e32 v22, 16, v20
	v_and_b32_e32 v23, 0xffff0000, v20
	v_pk_mul_f32 v[22:23], v[26:27], v[22:23]
	s_nop 0
	v_cvt_pk_bf16_f32 v20, v22, v23
	v_lshlrev_b32_e32 v22, 16, v21
	v_and_b32_e32 v23, 0xffff0000, v21
	v_pk_mul_f32 v[22:23], v[28:29], v[22:23]
	s_nop 0
	v_cvt_pk_bf16_f32 v21, v22, v23
	global_store_dwordx2 v[18:19], v[20:21], off offset:32
	s_waitcnt vmcnt(7)
	s_nop 1
	v_mov_b64_e32 v[20:21], v[210:211]
	v_lshlrev_b32_e32 v22, 16, v20
	v_and_b32_e32 v23, 0xffff0000, v20
	v_pk_mul_f32 v[22:23], v[30:31], v[22:23]
	s_nop 0
	v_cvt_pk_bf16_f32 v20, v22, v23
	v_lshlrev_b32_e32 v22, 16, v21
	v_and_b32_e32 v23, 0xffff0000, v21
	v_pk_mul_f32 v[22:23], v[32:33], v[22:23]
	s_nop 0
	v_cvt_pk_bf16_f32 v21, v22, v23
	global_store_dwordx2 v[18:19], v[20:21], off offset:48
	s_waitcnt vmcnt(7)
	s_nop 1
	v_mov_b64_e32 v[20:21], v[212:213]
	v_lshlrev_b32_e32 v22, 16, v20
	v_and_b32_e32 v23, 0xffff0000, v20
	v_lshlrev_b32_e32 v20, 16, v21
	v_and_b32_e32 v21, 0xffff0000, v21
	v_pk_mul_f32 v[2:3], v[2:3], v[22:23]
	v_pk_mul_f32 v[4:5], v[4:5], v[20:21]
	v_cvt_pk_bf16_f32 v2, v2, v3
	v_cvt_pk_bf16_f32 v3, v4, v5
	global_store_dwordx2 v[18:19], v[2:3], off offset:64
	s_waitcnt vmcnt(7)
	s_nop 1
	v_mov_b64_e32 v[2:3], v[214:215]
	v_lshlrev_b32_e32 v4, 16, v2
	v_and_b32_e32 v5, 0xffff0000, v2
	v_pk_mul_f32 v[4:5], v[6:7], v[4:5]
	s_nop 0
	v_cvt_pk_bf16_f32 v2, v4, v5
	v_lshlrev_b32_e32 v4, 16, v3
	v_and_b32_e32 v5, 0xffff0000, v3
	v_pk_mul_f32 v[4:5], v[8:9], v[4:5]
	s_nop 0
	v_cvt_pk_bf16_f32 v3, v4, v5
	global_store_dwordx2 v[18:19], v[2:3], off offset:80
	s_waitcnt vmcnt(7)
	s_nop 1
	v_mov_b64_e32 v[2:3], v[216:217]
	v_lshlrev_b32_e32 v4, 16, v2
	v_and_b32_e32 v5, 0xffff0000, v2
	v_pk_mul_f32 v[4:5], v[10:11], v[4:5]
	s_nop 0
	v_cvt_pk_bf16_f32 v2, v4, v5
	v_lshlrev_b32_e32 v4, 16, v3
	v_and_b32_e32 v5, 0xffff0000, v3
	v_pk_mul_f32 v[4:5], v[12:13], v[4:5]
	s_nop 0
	v_cvt_pk_bf16_f32 v3, v4, v5
	global_store_dwordx2 v[18:19], v[2:3], off offset:96
	s_waitcnt vmcnt(7)
	s_nop 1
	v_mov_b64_e32 v[2:3], v[218:219]
	v_lshlrev_b32_e32 v4, 16, v2
	v_and_b32_e32 v5, 0xffff0000, v2
	v_pk_mul_f32 v[4:5], v[14:15], v[4:5]
	s_nop 0
	v_cvt_pk_bf16_f32 v2, v4, v5
	v_lshlrev_b32_e32 v4, 16, v3
	v_and_b32_e32 v5, 0xffff0000, v3
	v_pk_mul_f32 v[4:5], v[16:17], v[4:5]
	s_nop 0
	v_cvt_pk_bf16_f32 v3, v4, v5
	global_store_dwordx2 v[18:19], v[2:3], off offset:112
	s_barrier
	s_load_dword s3, s[6:7], 0x0
	s_waitcnt lgkmcnt(0)
	s_add_i32 s2, s3, s2
	s_cmpk_gt_i32 s2, 0x3ff
	s_cbranch_scc1 .LBB0_102

; DI unsigned xb_ld(unsigned* p) { return __hip_atomic_load(p, __ATOMIC_RELAXED, __HIP_MEMORY_SCOPE_AGENT); }
; DI void xcd_barrier_complete(unsigned* bar, unsigned x, unsigned& nloc, unsigned& nx) {
;     ...
;     for (;;) {
;         sum = 0u; cnt = 0u; mine = 0u;
; #pragma unroll
;         for (unsigned j = 0; j < 16; ++j) { const unsigned c = xb_ld(&bar[XB_XCNT(j)]); sum += c; cnt += (c > 0u) ? 1u : 0u; mine = (j == x) ? c : mine; }
;         if (sum == G) break;
;         __builtin_amdgcn_s_sleep(1);
;         if ((++sp & 255u) == 0u) { if (xb_ld(&bar[XB_TMO])) break; if (sp > XB_SPIN_CAP) { atomicAdd(&bar[XB_TMO], 1u); break; } }
;     }
.LBB0_449:
	v_readlane_b32 s8, v254, 18
	v_readlane_b32 s9, v254, 19
	s_mov_b64 s[10:11], -1
	s_nop 3
	global_load_dword v0, v1, s[8:9] sc1
	v_readlane_b32 s8, v254, 20
	v_readlane_b32 s9, v254, 21
	s_nop 4
	global_load_dword v2, v1, s[8:9] sc1
	v_readlane_b32 s8, v254, 22
	v_readlane_b32 s9, v254, 23
	s_nop 1
	s_nop 2
	global_load_dword v3, v1, s[8:9] sc1
	v_readlane_b32 s8, v254, 24
	v_readlane_b32 s9, v254, 25
	s_nop 1
	s_nop 2
	global_load_dword v4, v1, s[8:9] sc1
	v_readlane_b32 s8, v254, 26
	v_readlane_b32 s9, v254, 27
	s_nop 1
	s_nop 2
	global_load_dword v5, v1, s[8:9] sc1
	v_readlane_b32 s8, v254, 28
	v_readlane_b32 s9, v254, 29
	s_nop 1
	s_nop 2
	global_load_dword v6, v1, s[8:9] sc1
	v_readlane_b32 s8, v254, 30
	v_readlane_b32 s9, v254, 31
	s_nop 1
	s_nop 2
	global_load_dword v7, v1, s[8:9] sc1
	v_readlane_b32 s8, v254, 32
	v_readlane_b32 s9, v254, 33
	s_nop 1
	s_nop 2
	global_load_dword v8, v1, s[8:9] sc1
	v_readlane_b32 s8, v254, 34
	v_readlane_b32 s9, v254, 35
	s_nop 1
	s_nop 2
	global_load_dword v9, v1, s[8:9] sc1
	v_readlane_b32 s8, v254, 36
	v_readlane_b32 s9, v254, 37
	s_nop 1
	s_nop 2
	global_load_dword v10, v1, s[8:9] sc1
	v_readlane_b32 s8, v254, 38
	v_readlane_b32 s9, v254, 39
	s_nop 1
	s_nop 2
	global_load_dword v11, v1, s[8:9] sc1
	v_readlane_b32 s8, v254, 40
	v_readlane_b32 s9, v254, 41
	s_nop 1
	s_nop 2
	global_load_dword v12, v1, s[8:9] sc1
	v_readlane_b32 s8, v254, 42
	v_readlane_b32 s9, v254, 43
	s_nop 1
	s_nop 2
	global_load_dword v13, v1, s[8:9] sc1
	v_readlane_b32 s8, v254, 44
	v_readlane_b32 s9, v254, 45
	s_nop 1
	s_nop 2
	global_load_dword v14, v1, s[8:9] sc1
	v_readlane_b32 s8, v254, 46
	v_readlane_b32 s9, v254, 47
	s_nop 1
	s_nop 2
	global_load_dword v15, v1, s[8:9] sc1
	v_readlane_b32 s8, v254, 48
	v_readlane_b32 s9, v254, 49
	s_nop 1
	s_nop 2
	global_load_dword v16, v1, s[8:9] sc1
	s_mov_b64 s[8:9], -1
	s_waitcnt vmcnt(0)
	v_add_u32_e32 v17, v2, v0
	v_add_u32_e32 v17, v17, v3
	v_add_u32_e32 v17, v17, v4
	v_add_u32_e32 v17, v17, v5
	v_add_u32_e32 v17, v17, v6
	v_add_u32_e32 v17, v17, v7
	v_add_u32_e32 v17, v17, v8
	v_add_u32_e32 v17, v17, v9
	v_add_u32_e32 v17, v17, v10
	v_add_u32_e32 v17, v17, v11
	v_add_u32_e32 v17, v17, v12
	v_add_u32_e32 v17, v17, v13
	v_add_u32_e32 v17, v17, v14
	v_add_u32_e32 v17, v17, v15
	v_add_u32_e32 v17, v17, v16
	v_cmp_eq_u32_e32 vcc, s14, v17
	s_cbranch_vccnz .LBB0_448
	s_and_b32 s8, s15, 0xff
	s_cmp_eq_u32 s8, 0
	s_mov_b64 s[8:9], -1
	s_mov_b64 s[12:13], -1
	s_sleep 1
	s_cbranch_scc1 .LBB0_453
	s_and_b64 vcc, exec, s[12:13]
	s_cbranch_vccz .LBB0_448
